# P4 sparse tile: mask-bit extraction hoisted under the QK MFMAs, masking in place
# speedup vs baseline: 1.0294x; 1.0009x over previous
.LBB0_2555:
	v_mov_b32_e32 v173, v125
	s_addk_i32 s71, 0x5000
	s_add_i32 s72, s72, 2
	s_cmpk_eq_u32 s71, 0xa000
	s_cbranch_scc0 .LBB0_2559
	s_branch .LBB0_2560
.LBB0_2556:
	s_setprio 1
	v_add_u32_e32 v170, s71, v141
	v_add_u32_e32 v169, s71, v139
	v_add_u32_e32 v168, s71, v137
	v_add_u32_e32 v167, s71, v127
	v_add_u32_e32 v171, s71, v166
	ds_read_b128 v[214:217], v170
	ds_read_b128 v[218:221], v169
	ds_read_b128 v[222:225], v170 offset:4096
	ds_read_b128 v[226:229], v169 offset:4096
	ds_read_b128 v[230:233], v168
	ds_read_b128 v[234:237], v168 offset:4096
	ds_read_b128 v[238:241], v167
	ds_read_b128 v[242:245], v167 offset:4096
	ds_read2_b32 v[172:173], v171 offset1:32
	s_cmp_lt_i32 s72, s52
	s_cselect_b64 s[90:91], -1, 0
	s_cmp_eq_u32 s52, s72
	s_cselect_b64 s[94:95], -1, 0
	s_cmp_eq_u32 s53, s72
	s_cselect_b64 vcc, -1, 0
	s_waitcnt lgkmcnt(8)
	v_mfma_f32_32x32x16_bf16 v[50:65], v[214:217], v[94:97], 0
	ds_read_b128 v[214:217], v170 offset:8192
	s_waitcnt lgkmcnt(8)
	v_mfma_f32_32x32x16_bf16 v[50:65], v[218:221], v[90:93], v[50:65]
	ds_read_b128 v[218:221], v170 offset:12288
	s_waitcnt lgkmcnt(2)
	v_lshrrev_b32_e32 v171, v134, v173
	v_lshrrev_b32_e32 v172, v134, v172
	v_cndmask_b32_e64 v171, 0, v171, s[90:91]
	v_cndmask_b32_e64 v173, -1, v121, s[94:95]
	v_and_b32_e32 v174, v172, v173
	v_cndmask_b32_e32 v172, -1, v121, vcc
	v_and_b32_e32 v175, v171, v172
	s_waitcnt lgkmcnt(8)
	v_mfma_f32_32x32x16_bf16 v[66:81], v[222:225], v[94:97], 0
	ds_read_b128 v[222:225], v169 offset:8192
	v_bfe_i32 v250, v174, 0, 1
	v_bfe_i32 v251, v174, 1, 1
	v_bfe_i32 v252, v174, 2, 1
	s_waitcnt lgkmcnt(8)
	v_mfma_f32_32x32x16_bf16 v[66:81], v[226:229], v[90:93], v[66:81]
	ds_read_b128 v[226:229], v169 offset:12288
	v_bfe_i32 v253, v174, 3, 1
	v_bfe_i32 v178, v174, 8, 1
	v_bfe_i32 v179, v174, 9, 1
	s_waitcnt lgkmcnt(8)
	v_mfma_f32_32x32x16_bf16 v[50:65], v[230:233], v[86:89], v[50:65]
	ds_read_b128 v[230:233], v168 offset:8192
	v_bfe_i32 v180, v174, 10, 1
	v_bfe_i32 v181, v174, 11, 1
	v_bfe_i32 v182, v174, 16, 1
	s_waitcnt lgkmcnt(8)
	v_mfma_f32_32x32x16_bf16 v[66:81], v[234:237], v[86:89], v[66:81]
	ds_read_b128 v[234:237], v168 offset:12288
	v_bfe_i32 v183, v174, 17, 1
	v_bfe_i32 v184, v174, 18, 1
	v_bfe_i32 v185, v174, 19, 1
	s_waitcnt lgkmcnt(8)
	v_mfma_f32_32x32x16_bf16 v[50:65], v[238:241], v[82:85], v[50:65]
	ds_read_b128 v[238:241], v167 offset:8192
	v_bfe_i32 v186, v174, 24, 1
	v_bfe_i32 v187, v174, 25, 1
	v_bfe_i32 v188, v174, 26, 1
	s_waitcnt lgkmcnt(8)
	v_mfma_f32_32x32x16_bf16 v[66:81], v[242:245], v[82:85], v[66:81]
	ds_read_b128 v[242:245], v167 offset:12288
	v_bfe_i32 v189, v174, 27, 1
	v_bfe_i32 v177, v175, 0, 1
	v_bfe_i32 v190, v175, 1, 1
	v_bfe_i32 v191, v175, 2, 1
	s_setprio 0
	v_bfe_i32 v171, v175, 3, 1
	v_bfe_i32 v172, v175, 8, 1
	v_bfe_i32 v173, v175, 9, 1
	v_bitop3_b32 v50, v50, s83, v250 bitop3:0xe4
	v_bitop3_b32 v51, v51, s83, v251 bitop3:0xe4
	v_bitop3_b32 v52, v52, s83, v252 bitop3:0xe4
	v_bitop3_b32 v53, v53, s83, v253 bitop3:0xe4
	v_bitop3_b32 v54, v54, s83, v178 bitop3:0xe4
	v_bitop3_b32 v55, v55, s83, v179 bitop3:0xe4
	v_bitop3_b32 v56, v56, s83, v180 bitop3:0xe4
	v_bitop3_b32 v57, v57, s83, v181 bitop3:0xe4
	v_bitop3_b32 v58, v58, s83, v182 bitop3:0xe4
	v_bitop3_b32 v59, v59, s83, v183 bitop3:0xe4
	v_bitop3_b32 v60, v60, s83, v184 bitop3:0xe4
	v_bitop3_b32 v61, v61, s83, v185 bitop3:0xe4
	v_bitop3_b32 v62, v62, s83, v186 bitop3:0xe4
	v_bitop3_b32 v63, v63, s83, v187 bitop3:0xe4
	v_bitop3_b32 v64, v64, s83, v188 bitop3:0xe4
	v_bitop3_b32 v65, v65, s83, v189 bitop3:0xe4
	v_bitop3_b32 v66, v66, s83, v177 bitop3:0xe4
	v_bitop3_b32 v67, v67, s83, v190 bitop3:0xe4
	v_bitop3_b32 v68, v68, s83, v191 bitop3:0xe4
	v_bitop3_b32 v69, v69, s83, v171 bitop3:0xe4
	v_bitop3_b32 v70, v70, s83, v172 bitop3:0xe4
	v_bitop3_b32 v71, v71, s83, v173 bitop3:0xe4
	v_bfe_i32 v250, v175, 10, 1
	v_bitop3_b32 v72, v72, s83, v250 bitop3:0xe4
	v_bfe_i32 v251, v175, 11, 1
	v_bitop3_b32 v73, v73, s83, v251 bitop3:0xe4
	v_bfe_i32 v252, v175, 16, 1
	v_bitop3_b32 v74, v74, s83, v252 bitop3:0xe4
	v_bfe_i32 v253, v175, 17, 1
	v_bitop3_b32 v75, v75, s83, v253 bitop3:0xe4
	v_bfe_i32 v178, v175, 18, 1
	v_bitop3_b32 v76, v76, s83, v178 bitop3:0xe4
	v_bfe_i32 v179, v175, 19, 1
	v_bitop3_b32 v77, v77, s83, v179 bitop3:0xe4
	v_bfe_i32 v180, v175, 24, 1
	v_bitop3_b32 v78, v78, s83, v180 bitop3:0xe4
	v_bfe_i32 v181, v175, 25, 1
	v_bitop3_b32 v79, v79, s83, v181 bitop3:0xe4
	v_bfe_i32 v182, v175, 26, 1
	v_bitop3_b32 v80, v80, s83, v182 bitop3:0xe4
	v_bfe_i32 v183, v175, 27, 1
	v_bitop3_b32 v81, v81, s83, v183 bitop3:0xe4
	v_max3_f32 v171, v213, v50, v66
	v_max3_f32 v172, v213, v51, v67
	v_max3_f32 v171, v171, v52, v68
	v_max3_f32 v172, v172, v53, v69
	v_max3_f32 v171, v171, v54, v70
	v_max3_f32 v172, v172, v55, v71
	v_max3_f32 v171, v171, v56, v72
	v_max3_f32 v172, v172, v57, v73
	v_max3_f32 v171, v171, v58, v74
	v_max3_f32 v172, v172, v59, v75
	v_max3_f32 v171, v171, v60, v76
	v_max3_f32 v172, v172, v61, v77
	v_max3_f32 v171, v171, v62, v78
	v_max3_f32 v172, v172, v63, v79
	v_max3_f32 v171, v171, v64, v80
	v_max3_f32 v172, v172, v65, v81
	v_max_f32_e32 v171, v171, v172
	v_mov_b32_e32 v172, v171
	s_nop 1
	v_permlane32_swap_b32_e32 v171, v172
	v_max3_f32 v173, v125, v171, v172
	v_cmp_gt_f32_e32 vcc, v173, v125
	s_cbranch_vccz .LBB0_2558
	v_sub_f32_e32 v174, v125, v173
	v_mul_f32_e32 v174, 0x3e38aa3b, v174
	v_exp_f32_e32 v174, v174
	s_nop 0
	v_pk_mul_f32 v[32:33], v[32:33], v[174:175] op_sel_hi:[1,0]
	v_pk_mul_f32 v[30:31], v[30:31], v[174:175] op_sel_hi:[1,0]
	v_pk_mul_f32 v[28:29], v[28:29], v[174:175] op_sel_hi:[1,0]
	v_pk_mul_f32 v[26:27], v[26:27], v[174:175] op_sel_hi:[1,0]
	v_pk_mul_f32 v[24:25], v[24:25], v[174:175] op_sel_hi:[1,0]
	v_pk_mul_f32 v[22:23], v[22:23], v[174:175] op_sel_hi:[1,0]
	v_pk_mul_f32 v[20:21], v[20:21], v[174:175] op_sel_hi:[1,0]
	v_pk_mul_f32 v[18:19], v[18:19], v[174:175] op_sel_hi:[1,0]
	v_pk_mul_f32 v[16:17], v[16:17], v[174:175] op_sel_hi:[1,0]
	v_pk_mul_f32 v[14:15], v[14:15], v[174:175] op_sel_hi:[1,0]
	v_pk_mul_f32 v[12:13], v[12:13], v[174:175] op_sel_hi:[1,0]
	v_pk_mul_f32 v[10:11], v[10:11], v[174:175] op_sel_hi:[1,0]
	v_pk_mul_f32 v[8:9], v[8:9], v[174:175] op_sel_hi:[1,0]
	v_pk_mul_f32 v[6:7], v[6:7], v[174:175] op_sel_hi:[1,0]
	v_pk_mul_f32 v[4:5], v[4:5], v[174:175] op_sel_hi:[1,0]
	v_pk_mul_f32 v[2:3], v[2:3], v[174:175] op_sel_hi:[1,0]
	v_mul_f32_e32 v34, v34, v174
.LBB0_2558:
	v_mul_f32_e32 v174, 0xbe38aa3b, v173
	v_fmamk_f32 v50, v50, 0x3e38aa3b, v174
	v_fmamk_f32 v51, v51, 0x3e38aa3b, v174
	v_fmamk_f32 v52, v52, 0x3e38aa3b, v174
	v_fmamk_f32 v53, v53, 0x3e38aa3b, v174
	v_fmamk_f32 v54, v54, 0x3e38aa3b, v174
	v_fmamk_f32 v55, v55, 0x3e38aa3b, v174
	v_fmamk_f32 v56, v56, 0x3e38aa3b, v174
	v_fmamk_f32 v57, v57, 0x3e38aa3b, v174
	v_exp_f32_e32 v50, v50
	v_exp_f32_e32 v51, v51
	v_exp_f32_e32 v52, v52
	v_exp_f32_e32 v53, v53
	v_exp_f32_e32 v54, v54
	v_exp_f32_e32 v55, v55
	v_exp_f32_e32 v56, v56
	v_exp_f32_e32 v57, v57
	v_cvt_pk_bf16_f32 v50, v50, v51
	v_cvt_pk_bf16_f32 v51, v52, v53
	v_cvt_pk_bf16_f32 v52, v54, v55
	v_cvt_pk_bf16_f32 v53, v56, v57
	s_setprio 1
	s_waitcnt lgkmcnt(0)
	v_mfma_f32_32x32x16_bf16 v[18:33], v[214:217], v[50:53], v[18:33]
	v_fmamk_f32 v58, v58, 0x3e38aa3b, v174
	v_fmamk_f32 v59, v59, 0x3e38aa3b, v174
	v_fmamk_f32 v60, v60, 0x3e38aa3b, v174
	v_fmamk_f32 v61, v61, 0x3e38aa3b, v174
	v_fmamk_f32 v62, v62, 0x3e38aa3b, v174
	v_fmamk_f32 v63, v63, 0x3e38aa3b, v174
	v_fmamk_f32 v64, v64, 0x3e38aa3b, v174
	v_mfma_f32_32x32x16_bf16 v[2:17], v[218:221], v[50:53], v[2:17]
	v_fmamk_f32 v65, v65, 0x3e38aa3b, v174
	v_exp_f32_e32 v58, v58
	v_exp_f32_e32 v59, v59
	v_exp_f32_e32 v60, v60
	v_exp_f32_e32 v61, v61
	v_exp_f32_e32 v62, v62
	v_exp_f32_e32 v63, v63
	v_mfma_f32_32x32x16_bf16 v[34:49], v[246:249], v[50:53], v[34:49]
	v_exp_f32_e32 v64, v64
	v_exp_f32_e32 v65, v65
	v_cvt_pk_bf16_f32 v58, v58, v59
	v_cvt_pk_bf16_f32 v59, v60, v61
	v_cvt_pk_bf16_f32 v60, v62, v63
	v_cvt_pk_bf16_f32 v61, v64, v65
	s_nop 1
	v_mfma_f32_32x32x16_bf16 v[18:33], v[222:225], v[58:61], v[18:33]
	v_fmamk_f32 v66, v66, 0x3e38aa3b, v174
	v_fmamk_f32 v67, v67, 0x3e38aa3b, v174
	v_fmamk_f32 v68, v68, 0x3e38aa3b, v174
	v_fmamk_f32 v69, v69, 0x3e38aa3b, v174
	v_fmamk_f32 v70, v70, 0x3e38aa3b, v174
	v_fmamk_f32 v71, v71, 0x3e38aa3b, v174
	v_fmamk_f32 v72, v72, 0x3e38aa3b, v174
	v_mfma_f32_32x32x16_bf16 v[2:17], v[226:229], v[58:61], v[2:17]
	v_fmamk_f32 v73, v73, 0x3e38aa3b, v174
	v_exp_f32_e32 v66, v66
	v_exp_f32_e32 v67, v67
	v_exp_f32_e32 v68, v68
	v_exp_f32_e32 v69, v69
	v_exp_f32_e32 v70, v70
	v_exp_f32_e32 v71, v71
	v_mfma_f32_32x32x16_bf16 v[34:49], v[246:249], v[58:61], v[34:49]
	v_exp_f32_e32 v72, v72
	v_exp_f32_e32 v73, v73
	v_cvt_pk_bf16_f32 v66, v66, v67
	v_cvt_pk_bf16_f32 v67, v68, v69
	v_cvt_pk_bf16_f32 v68, v70, v71
	v_cvt_pk_bf16_f32 v69, v72, v73
	s_nop 1
	v_mfma_f32_32x32x16_bf16 v[18:33], v[230:233], v[66:69], v[18:33]
	v_fmamk_f32 v74, v74, 0x3e38aa3b, v174
	v_fmamk_f32 v75, v75, 0x3e38aa3b, v174
	v_fmamk_f32 v76, v76, 0x3e38aa3b, v174
	v_fmamk_f32 v77, v77, 0x3e38aa3b, v174
	v_fmamk_f32 v78, v78, 0x3e38aa3b, v174
	v_fmamk_f32 v79, v79, 0x3e38aa3b, v174
	v_fmamk_f32 v80, v80, 0x3e38aa3b, v174
	v_mfma_f32_32x32x16_bf16 v[2:17], v[234:237], v[66:69], v[2:17]
	v_fmamk_f32 v81, v81, 0x3e38aa3b, v174
	v_exp_f32_e32 v74, v74
	v_exp_f32_e32 v75, v75
	v_exp_f32_e32 v76, v76
	v_exp_f32_e32 v77, v77
	v_exp_f32_e32 v78, v78
	v_exp_f32_e32 v79, v79
	v_mfma_f32_32x32x16_bf16 v[34:49], v[246:249], v[66:69], v[34:49]
	v_exp_f32_e32 v80, v80
	v_exp_f32_e32 v81, v81
	v_cvt_pk_bf16_f32 v74, v74, v75
	v_cvt_pk_bf16_f32 v75, v76, v77
	v_cvt_pk_bf16_f32 v76, v78, v79
	v_cvt_pk_bf16_f32 v77, v80, v81
	s_nop 1
	v_mfma_f32_32x32x16_bf16 v[18:33], v[238:241], v[74:77], v[18:33]
	v_mfma_f32_32x32x16_bf16 v[2:17], v[242:245], v[74:77], v[2:17]
	v_mfma_f32_32x32x16_bf16 v[34:49], v[246:249], v[74:77], v[34:49]
	s_setprio 0
	s_addk_i32 s71, 0x5000
	s_add_i32 s72, s72, 2
	s_cmpk_eq_u32 s71, 0xa000
	s_cbranch_scc1 .LBB0_2560
.LBB0_2559:
	v_mov_b32_e32 v125, v173
	s_cmp_gt_i32 s72, s52
	s_cbranch_scc1 .LBB0_2555
	s_branch .LBB0_2556
.LBB0_2560:
	s_add_i32 s69, s69, 4
	s_add_i32 s70, s70, 2
	s_and_b64 vcc, exec, s[54:55]
	s_cbranch_vccnz .LBB0_2563
	v_mov_b32_e32 v125, v173
	s_mov_b32 s9, s6
	s_branch .LBB0_2547
